# read-once f32 K/V cache streams (sample attention tiles, sample cross-attention fill) loaded with the nt hint so they stop evicting the reused prompt K/V from L2 (48 loads), on top of v039
# baseline (speedup 1.0000x reference)
; DI float fast_exp2(float x) { return __builtin_amdgcn_exp2f(x); }
; template <int VAR>
; DI void attn_segment(const Args& a, const Frame& F, int l, int qrow0, int qpos0, int hp, int ntile, int nf32, const float* ck, const float* cv, int prow0) {
;     ...
;     int lane = F.lane, tid = F.tid, wave = F.wave;
;     asm volatile("" : "+v"(lane), "+v"(tid)); asm volatile("" : "+s"(wave));
;     const int fr = lane & 15, fq = lane >> 4;
;     const int hh = wave >> 2, h = 2 * hp + hh, qr = (wave & 3) * 16;
;     const float slope2 = exp2f(-2.f * (float)(h + 1)) * LOG2E;
;     const bf16* qp = P + (size_t)(qrow0 + qr + fr) * INW + 256 + h * 64 + 8 * fq;
;     const bf16x8 q1 = ld8g(qp), q2 = ld8g(qp + 32);
;     const int qpos_l = qr + fr;
;     const float adv = 64.f * slope2, decay = fast_exp2(-adv);
;     AtState S; S.ref = -1e30f; S.l1 = 0.f; S.l2 = 0.f;
; #pragma unroll
;     for (int dt = 0; dt < 4; ++dt) { S.O1[dt] = (f32x4){0.f, 0.f, 0.f, 0.f}; S.O2[dt] = (f32x4){0.f, 0.f, 0.f, 0.f};
; #pragma unroll
;         for (int j = 0; j < 4; ++j) S.cinit[dt][j] = 0.f; }
;     if (nf32 == 0) {
;         const char* pb = (const char*)(P + (size_t)prow0 * INW + 512 + hp * 128);
;         const unsigned voff = (unsigned)((tid >> 4) * INW + (tid & 15) * 8) * 2u; constexpr size_t TSTR = (size_t)64 * INW * 2;
;         AtRawB ra, rb;
;         atb_issue(ra, pb, voff); atb_commit(ra, F.lds, tid);
;         const int nl = ntile - 1;
;         atb_issue(ra, pb + (size_t)(nl < 1 ? nl : 1) * TSTR, voff);
;         lds_barrier();
;         for (int kt = 0; kt < ntile; kt += 2) {
;             atb_issue(rb, pb + (size_t)(kt + 2 < nl ? kt + 2 : nl) * TSTR, voff);
;             attn_tile<VAR>(S, F.lds + (kt & 1) * AT_BUF, q1, q2, kt, kt + 1 == ntile, qpos0, qpos_l, slope2, adv, decay, hh, fr, fq);
;             atb_commit(ra, F.lds + ((kt + 1) & 1) * AT_BUF, tid);
;             lds_barrier();
;             if (kt + 1 >= ntile) break;
;             atb_issue(ra, pb + (size_t)(kt + 3 < nl ? kt + 3 : nl) * TSTR, voff);
;             attn_tile<VAR>(S, F.lds + ((kt + 1) & 1) * AT_BUF, q1, q2, kt + 1, kt + 2 == ntile, qpos0, qpos_l, slope2, adv, decay, hh, fr, fq);
;             atb_commit(rb, F.lds + (kt & 1) * AT_BUF, tid);
;             lds_barrier();
;         }
;     } else {
;         AtRaw raw;
.LBB0_1398:
	s_lshr_b32 s2, s21, 1
	s_lshl_b32 s16, s2, 19
	v_readlane_b32 s40, v250, 28
	s_lshl_b32 s0, s2, 6
	s_or_b32 s62, s16, s33
	v_readlane_b32 s46, v250, 34
	v_readlane_b32 s47, v250, 35
	s_and_b32 s1, s20, 1
	s_bitset1_b32 s0, 14
	s_lshl_b64 s[2:3], s[62:63], 2
	s_mov_b64 s[18:19], s[46:47]
	v_readlane_b32 s48, v250, 36
	v_readlane_b32 s49, v250, 37
	s_add_u32 s15, s18, s2
	v_readlane_b32 s50, v250, 38
	v_readlane_b32 s51, v250, 39
	v_readlane_b32 s52, v250, 40
	v_readlane_b32 s53, v250, 41
	v_readlane_b32 s54, v250, 42
	v_readlane_b32 s55, v250, 43
	s_mov_b64 s[20:21], s[48:49]
	s_addc_u32 s19, s19, s3
	s_add_u32 s20, s20, s2
	v_mov_b32_e32 v3, v160
	v_mov_b32_e32 v38, v0
	s_mov_b32 s2, s78
	s_addc_u32 s21, s21, s3
	s_ashr_i32 s14, s2, 2
	s_lshl_b32 s3, s1, 1
	s_add_i32 s17, s14, s3
	s_add_i32 s3, s17, 1
	v_cvt_f32_i32_e32 v40, s3
	s_mov_b64 s[22:23], s[50:51]
	s_lshl_b32 s22, s2, 4
	s_mov_b32 s2, 0xc2fc0000
	v_mul_f32_e32 v4, -2.0, v40
	v_cmp_gt_f32_e32 vcc, s2, v4
	s_and_b64 s[2:3], vcc, exec
	s_cselect_b32 s23, 0xffffffc0, 0
	s_lshl_b32 s2, s17, 6
	s_ashr_i32 s3, s2, 31
	s_lshl_b32 s17, s1, 9
	v_lshlrev_b32_e32 v4, 3, v38
	s_add_u32 s18, s15, s17
	v_and_b32_e32 v143, 0x78, v4
	s_addc_u32 s19, s19, 0
	v_lshlrev_b32_e32 v4, 2, v143
	v_mov_b32_e32 v5, v2
	v_ashrrev_i32_e32 v110, 4, v38
	v_add_u32_e32 v16, 0x200, v38
	v_lshl_add_u64 v[14:15], s[18:19], 0, v[4:5]
	v_ashrrev_i32_e32 v111, 31, v110
	v_ashrrev_i32_e32 v112, 4, v16
	s_add_u32 s18, s20, s17
	v_lshlrev_b64 v[18:19], 10, v[110:111]
	v_ashrrev_i32_e32 v113, 31, v112
	s_addc_u32 s19, s21, 0
	v_lshl_add_u64 v[6:7], v[14:15], 0, v[18:19]
	v_lshlrev_b64 v[30:31], 10, v[112:113]
	v_lshl_add_u64 v[4:5], s[18:19], 0, v[4:5]
	global_load_dwordx4 v[10:13], v[6:7], off offset:16 nt
	s_nop 0
	global_load_dwordx4 v[6:9], v[6:7], off nt
	v_lshl_add_u64 v[14:15], v[14:15], 0, v[30:31]
	v_lshl_add_u64 v[26:27], v[4:5], 0, v[18:19]
	v_lshl_add_u64 v[4:5], v[4:5], 0, v[30:31]
	v_and_b32_e32 v58, 15, v3
	v_cndmask_b32_e32 v41, 0, v201, vcc
	global_load_dwordx4 v[22:25], v[14:15], off offset:16 nt
	s_nop 0
	global_load_dwordx4 v[14:17], v[14:15], off nt
	s_waitcnt lgkmcnt(0)
	global_load_dwordx4 v[18:21], v[26:27], off nt
	s_nop 0
	global_load_dwordx4 v[26:29], v[26:27], off offset:16 nt
	s_nop 0
	global_load_dwordx4 v[30:33], v[4:5], off nt
	global_load_dwordx4 v[34:37], v[4:5], off offset:16 nt
	v_lshlrev_b32_e32 v5, 4, v38
	v_and_or_b32 v62, s22, 48, v58
	v_mov_b32_e32 v141, v2
	v_and_b32_e32 v38, 0xf0, v5
	v_or_b32_e32 v140, s0, v62
	v_fmac_f32_e32 v41, -2.0, v40
	v_readlane_b32 s18, v253, 62
	v_ashrrev_i32_e32 v59, 4, v3
	v_add_u32_e32 v202, 0, v38
	v_lshlrev_b64 v[38:39], 12, v[140:141]
	v_exp_f32_e32 v40, v41
	v_readlane_b32 s19, v253, 63
	v_lshlrev_b32_e32 v4, 3, v59
	v_ashrrev_i32_e32 v5, 31, v4
	v_lshl_add_u64 v[38:39], s[18:19], 0, v[38:39]
	v_lshl_add_u64 v[38:39], s[2:3], 1, v[38:39]
	v_lshl_add_u64 v[4:5], v[4:5], 1, v[38:39]
	v_ldexp_f32 v46, v40, s23
	global_load_dwordx4 v[38:41], v[4:5], off offset:512
	global_load_dwordx4 v[42:45], v[4:5], off offset:576
	s_lshl_b32 s1, s1, 8
	s_movk_i32 s15, 0x110
	s_add_u32 s1, s18, s1
	v_mul_lo_u32 v111, v110, s15
	v_mul_lo_u32 v203, v112, s15
	s_addc_u32 s15, s19, 0
	s_lshl_b32 s18, s14, 7
	s_lshl_b32 s0, s0, 12
	s_add_u32 s14, s1, s0
	s_addc_u32 s15, s15, 0
	s_add_u32 s0, s14, 0x400
	s_addc_u32 s1, s15, 0
	v_readlane_b32 s41, v250, 29
	s_add_u32 s14, s14, 0x600
	s_addc_u32 s15, s15, 0
	s_add_i32 s41, s18, 0
	v_readlane_b32 s18, v252, 59
	s_movk_i32 s20, 0x120
	s_add_i32 s62, s18, s16
	v_mul_lo_u32 v113, v110, s20
	v_add_u32_e32 v54, v202, v111
	v_mul_f32_e32 v114, 0x3fb8aa3b, v46
	v_mul_lo_u32 v205, v112, s20
	s_lshl_b64 s[18:19], s[62:63], 2
	v_add_u32_e32 v60, v202, v113
	v_mul_f32_e32 v204, 0x42800000, v114
	v_add_u32_e32 v4, v202, v205
	s_add_u32 s18, s17, s18
	v_add_u32_e32 v61, v202, v203
	v_exp_f32_e64 v116, -v204
	v_lshlrev_b32_e32 v142, 2, v59
	s_addc_u32 s19, 0, s19
	v_readlane_b32 s16, v252, 45
	s_add_u32 s16, s16, s18
	v_readlane_b32 s17, v252, 46
	v_and_b32_e32 v206, -16, v3
	s_addc_u32 s17, s17, s19
	v_mov_b32_e32 v5, v2
	v_readlane_b32 s42, v250, 30
	v_mul_u32_u24_e32 v207, 0x110, v58
	v_mov_b32_e32 v122, 0
	s_mov_b32 s40, 0
	v_mov_b32_e32 v118, v116
	v_mov_b32_e32 v119, v116
	v_sub_u32_e32 v210, v62, v142
	v_mul_f32_e32 v211, 0xc5000000, v114
	v_mov_b32_e32 v120, v116
	v_mov_b32_e32 v121, v116
	v_mov_b32_e32 v115, v114
	v_mov_b32_e32 v212, 0xf149f2ca
	s_movk_i32 s42, 0x800
	s_waitcnt vmcnt(0)
	v_cvt_pk_bf16_f32 v48, v10, v11
	v_cvt_pk_bf16_f32 v46, v6, v7
	v_cvt_pk_bf16_f32 v47, v8, v9
	v_cvt_pk_bf16_f32 v49, v12, v13
	ds_write_b128 v54, v[46:49]
	v_mov_b32_e32 v123, v122
	v_cvt_pk_bf16_f32 v52, v22, v23
	v_cvt_pk_bf16_f32 v46, v18, v19
	v_cvt_pk_bf16_f32 v47, v20, v21
	v_cvt_pk_bf16_f32 v48, v26, v27
	v_cvt_pk_bf16_f32 v49, v28, v29
	v_cvt_pk_bf16_f32 v54, v30, v31
	v_cvt_pk_bf16_f32 v55, v32, v33
	v_cvt_pk_bf16_f32 v56, v34, v35
	v_cvt_pk_bf16_f32 v57, v36, v37
	v_cvt_pk_bf16_f32 v50, v14, v15
	v_cvt_pk_bf16_f32 v51, v16, v17
	v_cvt_pk_bf16_f32 v53, v24, v25
	ds_write_b128 v60, v[46:49] offset:17408
	ds_write_b128 v61, v[50:53]
	ds_write_b128 v4, v[54:57] offset:17408
	v_bfe_u32 v4, v3, 2, 2
	v_or_b32_e32 v4, v142, v4
	s_waitcnt lgkmcnt(0)
	s_barrier
	v_lshlrev_b32_e32 v3, 3, v3
	v_mul_lo_u32 v209, v4, s20
	v_readlane_b32 s20, v252, 47
	v_mov_b32_e32 v4, v2
	v_and_b32_e32 v208, 24, v3
	s_add_u32 s18, s20, s18
	v_readlane_b32 s20, v252, 48
	v_mov_b32_e32 v3, v2
	v_mov_b64_e32 v[60:61], v[4:5]
	v_mov_b64_e32 v[56:57], v[4:5]
	v_mov_b64_e32 v[52:53], v[4:5]
	v_mov_b64_e32 v[48:49], v[4:5]
	s_addc_u32 s19, s20, s19
	v_mov_b64_e32 v[58:59], v[2:3]
	v_mov_b64_e32 v[54:55], v[2:3]
	v_mov_b64_e32 v[50:51], v[2:3]
	v_mov_b64_e32 v[46:47], v[2:3]
	v_mov_b32_e32 v4, v122
	v_mov_b32_e32 v5, v122
	v_mov_b32_e32 v124, v122
	v_mov_b32_e32 v125, v122
	v_mov_b32_e32 v126, v122
	v_mov_b32_e32 v127, v122
	v_mov_b32_e32 v128, v122
	v_mov_b32_e32 v129, v122
	v_mov_b32_e32 v130, v122
	v_mov_b32_e32 v131, v122
	v_mov_b32_e32 v132, v122
	v_mov_b32_e32 v133, v122
	v_mov_b32_e32 v134, v122
	v_mov_b32_e32 v135, v122
	v_mov_b32_e32 v136, v122
	v_mov_b32_e32 v137, v122
	v_mov_b32_e32 v138, v122
	v_mov_b32_e32 v139, v122
	v_mov_b32_e32 v144, v122
	v_mov_b32_e32 v145, v122
	v_mov_b32_e32 v146, v122
	v_mov_b32_e32 v147, v122
	v_mov_b32_e32 v148, v122
	v_mov_b32_e32 v149, v122
	v_mov_b32_e32 v150, v122
	v_mov_b32_e32 v151, v122
	v_mov_b32_e32 v152, v122
	v_mov_b32_e32 v153, v122
	v_mov_b32_e32 v154, v122
	v_mov_b32_e32 v155, v122
	v_mov_b32_e32 v156, v122
	v_mov_b32_e32 v157, v122
	v_readlane_b32 s43, v250, 31
	v_readlane_b32 s44, v250, 32
	v_readlane_b32 s45, v250, 33
	s_mov_b64 s[24:25], s[52:53]
	s_mov_b64 s[26:27], s[54:55]
	s_branch .LBB0_1400

; DI void at_issue(AtRaw& r, const void* kp, const void* vp, size_t rowstride_b, bool f32src, int tid) {
; #pragma unroll
;     for (int c = 0; c < 2; ++c) { const int e = tid + c * NTHR, key = e >> 4, c8 = (e & 15) * 8;
;         const char* k0 = (const char*)kp + key * rowstride_b + (f32src ? c8 * 4 : c8 * 2); const char* v0 = (const char*)vp + key * rowstride_b + (f32src ? c8 * 4 : c8 * 2);
;         const int o2 = f32src ? 16 : 0;
;         r.k[c][0] = *(const f32x4*)k0; r.k[c][1] = *(const f32x4*)(k0 + o2); r.v[c][0] = *(const f32x4*)v0; r.v[c][1] = *(const f32x4*)(v0 + o2); }
; }
; template <int VAR>
; DI void attn_segment(const Args& a, const Frame& F, int l, int qrow0, int qpos0, int hp, int ntile, int nf32, const float* ck, const float* cv, int prow0) {
;     ...
;             const bool more = kt + 1 < ntile; bool nf32s = false;
;             if (more) { const void *kp, *vp; size_t rs; at_src(kt + 1, nf32, ck, cv, P, prow0, hp, kp, vp, rs, nf32s); at_issue(raw, kp, vp, rs, nf32s, tid); }
.LBB0_1404:
	s_waitcnt vmcnt(7)
	v_lshlrev_b32_e32 v6, s29, v143
	v_mov_b32_e32 v7, v2
	s_waitcnt vmcnt(3)
	v_lshl_add_u64 v[14:15], s[34:35], 0, v[6:7]
	v_lshl_add_u64 v[16:17], s[38:39], 0, v[6:7]
	v_mad_i64_i32 v[10:11], s[34:35], s28, v110, v[14:15]
	s_waitcnt vmcnt(2)
	v_mad_i64_i32 v[22:23], s[34:35], s28, v110, v[16:17]
	global_load_dwordx4 v[6:9], v[10:11], off nt
	v_lshl_add_u64 v[10:11], v[10:11], 0, s[26:27]
	global_load_dwordx4 v[10:13], v[10:11], off nt
	s_nop 0
	global_load_dwordx4 v[18:21], v[22:23], off nt
	v_lshl_add_u64 v[22:23], v[22:23], 0, s[26:27]
	global_load_dwordx4 v[26:29], v[22:23], off nt
	v_mad_i64_i32 v[22:23], s[34:35], s28, v112, v[14:15]
	s_waitcnt vmcnt(4)
	v_mad_i64_i32 v[34:35], s[28:29], s28, v112, v[16:17]
	global_load_dwordx4 v[14:17], v[22:23], off nt
	v_lshl_add_u64 v[22:23], v[22:23], 0, s[26:27]
	global_load_dwordx4 v[22:25], v[22:23], off nt
	s_nop 0
	global_load_dwordx4 v[30:33], v[34:35], off nt
	v_lshl_add_u64 v[34:35], v[34:35], 0, s[26:27]
	global_load_dwordx4 v[34:37], v[34:35], off nt

; #define LAS __attribute__((address_space(3)))
; DI u32x4 pack8(f32x4 a, f32x4 b) { u32x4 w; w.x = pk2(a[0], a[1]); w.y = pk2(a[2], a[3]); w.z = pk2(b[0], b[1]); w.w = pk2(b[2], b[3]); return w; }
; DI void xattn_unit(const Args& a, const Frame& F, int l, int unit) {
;     ...
;     bf16x8 qc[4];
;     { const int rg = F.wave; const int row = row0 + 16 * (rg < nrg ? rg : 0) + fr;
; #pragma unroll
;       for (int ks = 0; ks < 4; ++ks) qc[ks] = ld8g(Q + (size_t)row * XW + h * 128 + 32 * ks + 8 * fq); }
;     if (prompt) {
;         const bf16* kb = (const bf16*)(a.ws + WS_MK) + ((size_t)l * (BP * NMEM) + b * NMEM) * XW + h * 128; const bf16* vb = (const bf16*)(a.ws + WS_MV) + ((size_t)l * (BP * NMEM) + b * NMEM) * XW + h * 128;
;         u32x4 kr[8], vr[8];
; #pragma unroll
;         for (int i = 0; i < 8; ++i) { const int e = tid + i * NTHR, key = e >> 4, c8 = (e & 15) * 8; kr[i] = *(const u32x4*)(kb + (size_t)key * XW + c8); vr[i] = *(const u32x4*)(vb + (size_t)key * XW + c8); }
; #pragma unroll
;         for (int i = 0; i < 8; ++i) { const int e = tid + i * NTHR, key = e >> 4, c8 = (e & 15) * 8;
;             *(LAS u32x4*)(F.lds + XA_K + key * 272 + c8 * 2) = kr[i]; *(LAS u32x4*)(F.lds + XA_V + key * 288 + c8 * 2) = vr[i]; }
;     } else {
;         const float* kb = a.in[I_CMK] + ((size_t)(l * BS + b) * NMEM * 4 + h) * 128; const float* vb = a.in[I_CMV] + ((size_t)(l * BS + b) * NMEM * 4 + h) * 128;
; #pragma unroll
;         for (int hb = 0; hb < 2; ++hb) {
;             f32x4 kr[4][2], vr[4][2];
; #pragma unroll
;             for (int i = 0; i < 4; ++i) { const int e = tid + (hb * 4 + i) * NTHR, key = e >> 4, c8 = (e & 15) * 8; const f32x4* k4 = (const f32x4*)(kb + (size_t)key * 512 + c8); const f32x4* v4 = (const f32x4*)(vb + (size_t)key * 512 + c8);
;                 kr[i][0] = k4[0]; kr[i][1] = k4[1]; vr[i][0] = v4[0]; vr[i][1] = v4[1]; }
; #pragma unroll
;             for (int i = 0; i < 4; ++i) { const int e = tid + (hb * 4 + i) * NTHR, key = e >> 4, c8 = (e & 15) * 8;
;                 *(LAS u32x4*)(F.lds + XA_K + key * 272 + c8 * 2) = pack8(kr[i][0], kr[i][1]); *(LAS u32x4*)(F.lds + XA_V + key * 288 + c8 * 2) = pack8(vr[i][0], vr[i][1]); }
.LBB0_2034:
	v_and_b32_e32 v99, 15, v95
	s_cmp_lt_i32 s78, s8
	s_cselect_b32 s6, s12, 0
	v_add_u32_e32 v94, s9, v99
	v_add_u32_e32 v4, s6, v94
	s_waitcnt lgkmcnt(0)
	v_ashrrev_i32_e32 v5, 31, v4
	s_lshl_b32 s6, s14, 7
	v_ashrrev_i32_e32 v96, 4, v95
	v_lshlrev_b64 v[4:5], 10, v[4:5]
	s_and_b32 s14, s6, 0x180
	v_lshl_add_u64 v[4:5], s[18:19], 0, v[4:5]
	s_lshl_b32 s62, s14, 1
	v_lshlrev_b32_e32 v68, 3, v96
	v_lshl_add_u64 v[4:5], v[4:5], 0, s[62:63]
	v_ashrrev_i32_e32 v69, 31, v68
	v_lshl_add_u64 v[4:5], v[68:69], 1, v[4:5]
	global_load_dwordx4 v[32:35], v[4:5], off
	global_load_dwordx4 v[28:31], v[4:5], off offset:64
	global_load_dwordx4 v[24:27], v[4:5], off offset:128
	global_load_dwordx4 v[20:23], v[4:5], off offset:192
	v_ashrrev_i32_e32 v4, 4, v8
	s_and_b64 vcc, exec, s[0:1]
	s_movk_i32 s0, 0x110
	v_ashrrev_i32_e32 v5, 31, v4
	v_mul_lo_u32 v98, v4, s0
	s_movk_i32 s0, 0x120
	v_lshlrev_b64 v[86:87], 9, v[4:5]
	v_lshlrev_b32_e32 v9, 4, v8
	v_add_u32_e32 v5, 0x200, v8
	v_add_u32_e32 v6, 0x400, v8
	v_add_u32_e32 v7, 0x600, v8
	v_mul_lo_u32 v97, v4, s0
	v_add_u32_e32 v4, 0x800, v8
	v_add_u32_e32 v10, 0xa00, v8
	v_add_u32_e32 v11, 0xc00, v8
	v_add_u32_e32 v73, 0xe00, v8
	s_mov_b64 s[6:7], -1
	v_and_b32_e32 v70, 0xf0, v9
	v_ashrrev_i32_e32 v84, 4, v5
	v_ashrrev_i32_e32 v82, 4, v6
	v_ashrrev_i32_e32 v80, 4, v7
	v_ashrrev_i32_e32 v78, 4, v4
	v_ashrrev_i32_e32 v76, 4, v10
	v_ashrrev_i32_e32 v74, 4, v11
	v_ashrrev_i32_e32 v72, 4, v73
	s_cbranch_vccz .LBB0_2036
	s_add_i32 s0, s13, s10
	s_ashr_i32 s1, s0, 31
	s_lshl_b64 s[0:1], s[0:1], 19
	s_lshl_b32 s6, s14, 2
	s_or_b32 s0, s0, s6
	v_readlane_b32 s16, v250, 10
	v_readlane_b32 s17, v250, 11
	s_add_u32 s6, s16, s0
	v_readlane_b32 s18, v250, 12
	s_addc_u32 s7, s17, s1
	v_readlane_b32 s19, v250, 13
	s_add_u32 s0, s18, s0
	v_lshlrev_b32_e32 v4, 5, v8
	s_addc_u32 s1, s19, s1
	v_and_b32_e32 v4, 0x1e0, v4
	v_mov_b32_e32 v5, v2
	v_lshl_add_u64 v[88:89], s[6:7], 0, v[4:5]
	v_lshl_add_u64 v[90:91], s[0:1], 0, v[4:5]
	v_lshlrev_b64 v[4:5], 2, v[86:87]
	v_and_b32_e32 v71, 0xf0, v9
	v_lshl_add_u64 v[8:9], v[88:89], 0, v[4:5]
	v_lshl_add_u64 v[16:17], v[90:91], 0, v[4:5]
	global_load_dwordx4 v[4:7], v[8:9], off offset:16 nt
	s_nop 0
	global_load_dwordx4 v[8:11], v[8:9], off nt
	s_nop 0
	global_load_dwordx4 v[12:15], v[16:17], off offset:16 nt
	s_nop 0
	global_load_dwordx4 v[16:19], v[16:17], off nt
	v_ashrrev_i32_e32 v85, 31, v84
	v_lshlrev_b64 v[36:37], 11, v[84:85]
	v_lshl_add_u64 v[40:41], v[88:89], 0, v[36:37]
	v_lshl_add_u64 v[48:49], v[90:91], 0, v[36:37]
	global_load_dwordx4 v[36:39], v[40:41], off offset:16 nt
	s_nop 0
	global_load_dwordx4 v[40:43], v[40:41], off nt
	s_nop 0
	global_load_dwordx4 v[44:47], v[48:49], off offset:16 nt
	s_nop 0
	global_load_dwordx4 v[48:51], v[48:49], off nt
	v_ashrrev_i32_e32 v83, 31, v82
	v_lshlrev_b64 v[52:53], 11, v[82:83]
	v_lshl_add_u64 v[56:57], v[88:89], 0, v[52:53]
	v_lshl_add_u64 v[64:65], v[90:91], 0, v[52:53]
	global_load_dwordx4 v[52:55], v[56:57], off offset:16 nt
	s_nop 0
	global_load_dwordx4 v[56:59], v[56:57], off nt
	s_nop 0
	global_load_dwordx4 v[60:63], v[64:65], off offset:16 nt
	s_nop 0
	global_load_dwordx4 v[64:67], v[64:65], off nt
	v_ashrrev_i32_e32 v81, 31, v80
	v_lshlrev_b64 v[92:93], 11, v[80:81]
	v_lshl_add_u64 v[104:105], v[88:89], 0, v[92:93]
	v_lshl_add_u64 v[92:93], v[90:91], 0, v[92:93]
	global_load_dwordx4 v[100:103], v[104:105], off offset:16 nt
	s_nop 0
	global_load_dwordx4 v[104:107], v[104:105], off nt
	s_nop 0
	global_load_dwordx4 v[108:111], v[92:93], off offset:16 nt
	global_load_dwordx4 v[112:115], v[92:93], off nt
	v_readlane_b32 s6, v252, 58
	s_movk_i32 s1, 0x110
	s_movk_i32 s0, 0x120
	v_ashrrev_i32_e32 v79, 31, v78
	v_ashrrev_i32_e32 v77, 31, v76
	v_ashrrev_i32_e32 v75, 31, v74
	v_ashrrev_i32_e32 v92, 4, v73
	v_ashrrev_i32_e32 v93, 31, v92
	v_readlane_b32 s30, v250, 24
	v_readlane_b32 s31, v250, 25
	v_readlane_b32 s30, v249, 21
	v_readlane_b32 s18, v252, 21
	v_readlane_b32 s20, v250, 14
	v_readlane_b32 s21, v250, 15
	v_readlane_b32 s22, v250, 16
	v_readlane_b32 s23, v250, 17
	v_readlane_b32 s24, v250, 18
	v_readlane_b32 s25, v250, 19
	v_readlane_b32 s26, v250, 20
	v_readlane_b32 s27, v250, 21
	v_readlane_b32 s28, v250, 22
	v_readlane_b32 s29, v250, 23
	v_readlane_b32 s31, v249, 22
	v_readlane_b32 s19, v252, 22
	s_waitcnt vmcnt(14)
	v_cvt_pk_bf16_f32 v8, v8, v9
	v_cvt_pk_bf16_f32 v9, v10, v11
	v_cvt_pk_bf16_f32 v10, v4, v5
	v_cvt_pk_bf16_f32 v11, v6, v7
	v_add3_u32 v4, 0, v98, v71
	ds_write_b128 v4, v[8:11]
	s_waitcnt vmcnt(12)
	v_cvt_pk_bf16_f32 v4, v16, v17
	v_cvt_pk_bf16_f32 v5, v18, v19
	v_cvt_pk_bf16_f32 v6, v12, v13
	v_cvt_pk_bf16_f32 v7, v14, v15
	v_add3_u32 v8, s6, v97, v71
	ds_write_b128 v8, v[4:7]
	v_mul_lo_u32 v8, v84, s1
	s_waitcnt vmcnt(10)
; #define LAS __attribute__((address_space(3)))
; DI u32x4 pack8(f32x4 a, f32x4 b) { u32x4 w; w.x = pk2(a[0], a[1]); w.y = pk2(a[2], a[3]); w.z = pk2(b[0], b[1]); w.w = pk2(b[2], b[3]); return w; }
; DI void xattn_unit(const Args& a, const Frame& F, int l, int unit) {
;     ...
;         for (int hb = 0; hb < 2; ++hb) {
;             f32x4 kr[4][2], vr[4][2];
; #pragma unroll
;             for (int i = 0; i < 4; ++i) { const int e = tid + (hb * 4 + i) * NTHR, key = e >> 4, c8 = (e & 15) * 8; const f32x4* k4 = (const f32x4*)(kb + (size_t)key * 512 + c8); const f32x4* v4 = (const f32x4*)(vb + (size_t)key * 512 + c8);
;                 kr[i][0] = k4[0]; kr[i][1] = k4[1]; vr[i][0] = v4[0]; vr[i][1] = v4[1]; }
; #pragma unroll
;             for (int i = 0; i < 4; ++i) { const int e = tid + (hb * 4 + i) * NTHR, key = e >> 4, c8 = (e & 15) * 8;
;                 *(LAS u32x4*)(F.lds + XA_K + key * 272 + c8 * 2) = pack8(kr[i][0], kr[i][1]); *(LAS u32x4*)(F.lds + XA_V + key * 288 + c8 * 2) = pack8(vr[i][0], vr[i][1]); }
	v_cvt_pk_bf16_f32 v4, v40, v41
	v_cvt_pk_bf16_f32 v5, v42, v43
	v_cvt_pk_bf16_f32 v6, v36, v37
	v_cvt_pk_bf16_f32 v7, v38, v39
	v_add3_u32 v8, 0, v8, v71
	ds_write_b128 v8, v[4:7]
	v_mul_lo_u32 v8, v84, s0
	s_waitcnt vmcnt(8)
	v_cvt_pk_bf16_f32 v4, v48, v49
	v_cvt_pk_bf16_f32 v5, v50, v51
	v_cvt_pk_bf16_f32 v6, v44, v45
	v_cvt_pk_bf16_f32 v7, v46, v47
	v_add3_u32 v8, s6, v8, v71
	ds_write_b128 v8, v[4:7]
	v_mul_lo_u32 v8, v82, s1
	s_waitcnt vmcnt(6)
	v_cvt_pk_bf16_f32 v4, v56, v57
	v_cvt_pk_bf16_f32 v5, v58, v59
	v_cvt_pk_bf16_f32 v6, v52, v53
	v_cvt_pk_bf16_f32 v7, v54, v55
	v_add3_u32 v8, 0, v8, v71
	ds_write_b128 v8, v[4:7]
	v_mul_lo_u32 v8, v82, s0
	s_waitcnt vmcnt(4)
	v_cvt_pk_bf16_f32 v4, v64, v65
	v_cvt_pk_bf16_f32 v5, v66, v67
	v_cvt_pk_bf16_f32 v6, v60, v61
	v_cvt_pk_bf16_f32 v7, v62, v63
	v_add3_u32 v8, s6, v8, v71
	ds_write_b128 v8, v[4:7]
	v_mul_lo_u32 v8, v80, s1
	s_waitcnt vmcnt(2)
	v_cvt_pk_bf16_f32 v4, v104, v105
	v_cvt_pk_bf16_f32 v5, v106, v107
	v_cvt_pk_bf16_f32 v6, v100, v101
	v_cvt_pk_bf16_f32 v7, v102, v103
	v_add3_u32 v8, 0, v8, v71
	ds_write_b128 v8, v[4:7]
	v_mul_lo_u32 v8, v80, s0
	s_waitcnt vmcnt(0)
	v_cvt_pk_bf16_f32 v4, v112, v113
	v_cvt_pk_bf16_f32 v5, v114, v115
	v_cvt_pk_bf16_f32 v6, v108, v109
	v_cvt_pk_bf16_f32 v7, v110, v111
	v_add3_u32 v8, s6, v8, v71
	ds_write_b128 v8, v[4:7]
	v_lshlrev_b64 v[4:5], 11, v[78:79]
	v_lshl_add_u64 v[6:7], v[88:89], 0, v[4:5]
	v_lshl_add_u64 v[8:9], v[90:91], 0, v[4:5]
	global_load_dwordx4 v[12:15], v[6:7], off offset:16 nt
	global_load_dwordx4 v[16:19], v[6:7], off nt
	s_nop 0
	global_load_dwordx4 v[4:7], v[8:9], off offset:16 nt
	s_nop 0
	global_load_dwordx4 v[8:11], v[8:9], off nt
	v_lshlrev_b64 v[36:37], 11, v[76:77]
	v_lshl_add_u64 v[38:39], v[88:89], 0, v[36:37]
	v_lshl_add_u64 v[40:41], v[90:91], 0, v[36:37]
	global_load_dwordx4 v[44:47], v[38:39], off offset:16 nt
	global_load_dwordx4 v[48:51], v[38:39], off nt
	s_nop 0
	global_load_dwordx4 v[36:39], v[40:41], off offset:16 nt
	s_nop 0
	global_load_dwordx4 v[40:43], v[40:41], off nt
	v_lshlrev_b64 v[52:53], 11, v[74:75]
	v_lshl_add_u64 v[54:55], v[88:89], 0, v[52:53]
	v_lshl_add_u64 v[56:57], v[90:91], 0, v[52:53]
	global_load_dwordx4 v[60:63], v[54:55], off offset:16 nt
	global_load_dwordx4 v[64:67], v[54:55], off nt
	s_nop 0
	global_load_dwordx4 v[52:55], v[56:57], off offset:16 nt
	s_nop 0
	global_load_dwordx4 v[56:59], v[56:57], off nt
	v_lshlrev_b64 v[100:101], 11, v[92:93]
	v_lshl_add_u64 v[102:103], v[88:89], 0, v[100:101]
	v_lshl_add_u64 v[108:109], v[90:91], 0, v[100:101]
	global_load_dwordx4 v[88:91], v[102:103], off offset:16 nt
	s_nop 0
	global_load_dwordx4 v[100:103], v[102:103], off nt
	s_nop 0
	global_load_dwordx4 v[104:107], v[108:109], off offset:16 nt
	s_nop 0
	global_load_dwordx4 v[108:111], v[108:109], off nt
	s_waitcnt vmcnt(14)
	v_cvt_pk_bf16_f32 v16, v16, v17
	v_cvt_pk_bf16_f32 v17, v18, v19
	v_cvt_pk_bf16_f32 v18, v12, v13
	v_mul_lo_u32 v12, v78, s1
	s_waitcnt vmcnt(12)
	v_cvt_pk_bf16_f32 v8, v8, v9
	v_cvt_pk_bf16_f32 v9, v10, v11
	v_cvt_pk_bf16_f32 v10, v4, v5
	v_mul_lo_u32 v4, v78, s0
	v_cvt_pk_bf16_f32 v19, v14, v15
	v_add3_u32 v12, 0, v12, v71
	v_cvt_pk_bf16_f32 v11, v6, v7
	v_add3_u32 v4, s6, v4, v71
	ds_write_b128 v12, v[16:19]
	ds_write_b128 v4, v[8:11]
	v_mul_lo_u32 v8, v76, s1
	s_waitcnt vmcnt(10)
	v_cvt_pk_bf16_f32 v4, v48, v49
	v_cvt_pk_bf16_f32 v5, v50, v51
	v_cvt_pk_bf16_f32 v6, v44, v45
	v_cvt_pk_bf16_f32 v7, v46, v47
	v_add3_u32 v8, 0, v8, v71
	ds_write_b128 v8, v[4:7]
	v_mul_lo_u32 v8, v76, s0
	s_waitcnt vmcnt(8)
	v_cvt_pk_bf16_f32 v4, v40, v41
	v_cvt_pk_bf16_f32 v5, v42, v43
	v_cvt_pk_bf16_f32 v6, v36, v37
	v_cvt_pk_bf16_f32 v7, v38, v39
	v_add3_u32 v8, s6, v8, v71
	ds_write_b128 v8, v[4:7]
	v_mul_lo_u32 v8, v74, s1
	s_waitcnt vmcnt(6)
	v_cvt_pk_bf16_f32 v4, v64, v65
	v_cvt_pk_bf16_f32 v5, v66, v67
	v_cvt_pk_bf16_f32 v6, v60, v61
	v_cvt_pk_bf16_f32 v7, v62, v63
	v_add3_u32 v8, 0, v8, v71
	ds_write_b128 v8, v[4:7]
	v_mul_lo_u32 v8, v74, s0
	s_waitcnt vmcnt(4)
	v_cvt_pk_bf16_f32 v4, v56, v57
	v_cvt_pk_bf16_f32 v5, v58, v59
	v_cvt_pk_bf16_f32 v6, v52, v53
	v_cvt_pk_bf16_f32 v7, v54, v55
	v_add3_u32 v8, s6, v8, v71
	ds_write_b128 v8, v[4:7]
	v_mul_lo_u32 v8, v92, s1
	s_waitcnt vmcnt(2)
	v_cvt_pk_bf16_f32 v4, v100, v101
	v_cvt_pk_bf16_f32 v5, v102, v103
	v_cvt_pk_bf16_f32 v6, v88, v89
	v_cvt_pk_bf16_f32 v7, v90, v91
	v_add3_u32 v8, 0, v8, v71
	ds_write_b128 v8, v[4:7]
	s_waitcnt vmcnt(0)
	v_cvt_pk_bf16_f32 v4, v108, v109
	v_cvt_pk_bf16_f32 v5, v110, v111
	v_cvt_pk_bf16_f32 v6, v104, v105
	v_cvt_pk_bf16_f32 v7, v106, v107
	s_mov_b64 s[6:7], 0
